# phase 3b: all 256 workgroups share the layer-1 weight conversion and modulation GEMV after their sequential role (wb0 = 0)
# baseline (speedup 1.0000x reference)
; __device__ __forceinline__ void phase_convert(const Params& p, unsigned char* lds, const int part, const int wb0, const int nwb) {
;     const int lane = threadIdx.x & 63, wave = threadIdx.x >> 6;
;     float* scr = (float*)(lds + wave * 16384);
;     const int gw = ((int)blockIdx.x - wb0) * 8 + wave, NGW = nwb * 8;
;     constexpr int I_IN = 32 * 161, I_OUT = 32 * 64, I_UP = 32 * 256, I_DN = 128 * 64, I_QKV = 32 * 192, I_NO = 32 * 64;
;     bf16_t* win = (bf16_t*)(p.ws + WS_WIN); bf16_t* wout = (bf16_t*)(p.ws + WS_WOUT); bf16_t* wup = (bf16_t*)(p.ws + WS_WUP);
;     bf16_t* wdn = (bf16_t*)(p.ws + WS_WDN); bf16_t* wqkv = (bf16_t*)(p.ws + WS_WQKV); bf16_t* wno = (bf16_t*)(p.ws + WS_WNO);
;     __syncthreads();
;     if (part == 0) {
;         for (int it = gw; it < I_IN + I_OUT + I_UP + I_DN; it += NGW) {
;             int r = it;
;             if (r < I_IN) { const int kb = r / 161, nb = r % 161, n0 = 32 * nb;
;                 if (n0 >= 1024 && n0 < 2048) { transpose_item(p.ev_w_in, D, 5152, (bf16_t*)(p.ws + WS_WV0), kb, n0, n0 - 1024, scr, lane); continue; }
;                 const int dn = n0 < 1024 ? n0 : (n0 < 3072 ? n0 - 1024 : (n0 == 3072 ? C_GL : (n0 < 4128 ? n0 - 3104 + C_XR : n0 - 4128 + C_YR)));
;                 transpose_item(p.ev_w_in, D, 5152, win, kb, n0, dn, scr, lane); continue; } r -= I_IN;
;             if (r < I_OUT) { transpose_item(p.ev_w_out, D, D, wout, r / 64, 32 * (r % 64), 32 * (r % 64), scr, lane); continue; } r -= I_OUT;
;             if (r < I_UP) { transpose_item(p.mlp_up, D, DFF, wup, r / 256, 32 * (r % 256), 32 * (r % 256), scr, lane); continue; } r -= I_UP;
;             transpose_item(p.mlp_down, DFF, D, wdn, r / 64, 32 * (r % 64), 32 * (r % 64), scr, lane);
;         }
;         for (int m = (int)blockIdx.x - wb0; m < 32; m += nwb) { const float* src = ((m & 1) ? p.w_x : p.w_a) + (size_t)(m >> 1) * 16384; bf16_t* img = (bf16_t*)(p.ws + WS_LRUW) + (size_t)m * (128 * 136);
;             for (int e = threadIdx.x; e < 16384; e += 512) { const int ii = e >> 7, j = e & 127; img[j * 136 + ii] = (bf16_t)f2bf(src[e]); }
; __global__ void __launch_bounds__(512, 2) fwd_megakernel(Params p) {
;     ...
;         { const int wb0 = gridDim.x >= 256 ? 128 : 0, nwb = gridDim.x - wb0; if ((int)blockIdx.x >= wb0) { phase_convert(p, lds, 1, wb0, nwb); phase_mod(p, lds, 1, wb0, nwb); } } } } } SEAM(3);
.LBB0_570:
	s_cmpk_gt_u32 s82, 0xff
	s_mov_b32 s10, 0
	s_cmp_ge_i32 s92, s10
	s_cbranch_scc0 .LBB0_601
	v_lshrrev_b32_e32 v0, 6, v162
	s_sub_i32 s18, s92, s10
	s_waitcnt vmcnt(2)
	v_lshl_add_u32 v22, s18, 3, v0
	s_movk_i32 s0, 0x6000
	v_cmp_gt_u32_e32 vcc, s0, v22
	s_sub_i32 s19, s82, s10
	s_barrier
	s_and_saveexec_b64 s[0:1], vcc
	s_cbranch_execz .LBB0_586
	v_lshl_add_u32 v14, v0, 14, 0
	v_and_b32_e32 v0, 31, v162
	v_lshlrev_b32_e32 v16, 2, v0
	v_lshlrev_b32_e32 v0, 1, v107
	v_mov_b32_e32 v1, 0
	v_lshl_add_u64 v[8:9], s[90:91], 0, v[0:1]
	s_mov_b64 s[2:3], 0xb600000
	v_readlane_b32 s52, v241, 17
	v_lshl_add_u64 v[2:3], v[8:9], 0, s[2:3]
	s_mov_b64 s[2:3], 0x9e00000
	v_readlane_b32 s64, v241, 29
	v_readlane_b32 s65, v241, 30
	v_lshl_add_u64 v[4:5], v[8:9], 0, s[2:3]
	s_mov_b64 s[2:3], 0x7e00000
	v_readlane_b32 s66, v241, 31
	v_readlane_b32 s67, v241, 32
	s_mov_b64 s[12:13], s[64:65]
	v_lshrrev_b32_e32 v24, 3, v161
	v_lshl_add_u64 v[6:7], v[8:9], 0, s[2:3]
	s_mov_b64 s[2:3], 0x3e00000
	v_mov_b32_e32 v17, v1
	s_mov_b64 s[14:15], s[66:67]
	v_lshlrev_b32_e32 v0, 2, v24
	v_add3_u32 v23, v14, v109, v16
	v_lshl_add_u64 v[8:9], v[8:9], 0, s[2:3]
	v_lshl_add_u64 v[10:11], s[12:13], 0, v[16:17]
	v_lshl_add_u64 v[12:13], s[38:39], 0, v[16:17]
	s_mov_b64 s[2:3], 0x4000000
	v_add3_u32 v25, v14, v105, v0
	v_lshl_add_u64 v[14:15], s[14:15], 0, v[16:17]
	v_lshl_add_u64 v[16:17], s[36:37], 0, v[16:17]
	v_lshl_add_u64 v[12:13], v[12:13], 0, s[2:3]
	s_lshl_b32 s11, s19, 3
	v_or_b32_e32 v26, 8, v24
	v_or_b32_e32 v27, 16, v24
	v_or_b32_e32 v28, 24, v24
	v_lshl_add_u64 v[16:17], v[16:17], 0, s[2:3]
	v_lshlrev_b32_e32 v29, 5, v22
	s_lshl_b32 s12, s19, 8
	s_mov_b64 s[2:3], 0
	s_movk_i32 s13, 0x1fff
	s_movk_i32 s14, 0x3fff
	s_movk_i32 s15, 0x57ff
	s_mov_b32 s16, 0xc000
	s_mov_b32 s17, 0x18000
	s_mov_b32 s20, 0x24000
	s_mov_b32 s21, 0x30000
	s_mov_b32 s22, 0x3c000
	s_mov_b32 s23, 0x48000
	s_mov_b32 s24, 0x54000
	s_mov_b32 s25, 0x60000
	s_mov_b32 s26, 0x6c000
	s_mov_b32 s27, 0x78000
	s_mov_b32 s28, 0x84000
	s_mov_b32 s29, 0x90000
	s_mov_b32 s30, 0x9c000
	s_mov_b32 s31, 0xa8000
	s_mov_b32 s33, 0xb4000
	s_mov_b32 s34, 0xc0000
	s_mov_b32 s35, 0xcc000
	s_mov_b32 s36, 0xd8000
	s_mov_b32 s37, 0xe4000
	s_mov_b32 s38, 0xf0000
	s_mov_b32 s39, 0xfc000
	s_mov_b32 s40, 0x108000
	s_mov_b32 s41, 0x114000
	s_mov_b32 s42, 0x120000
	s_mov_b32 s43, 0x12c000
	s_mov_b32 s44, 0x138000
	s_mov_b32 s45, 0x144000
	s_mov_b32 s46, 0x150000
	s_mov_b32 s47, 0x15c000
	s_mov_b32 s50, 0x168000
	s_mov_b32 s51, 0x174000
	s_movk_i32 s52, 0x5fff
	v_add_u32_e32 v30, 0x400, v23
	v_add_u32_e32 v31, 0x800, v23
	v_add_u32_e32 v32, 0xc00, v23
	v_add_u32_e32 v33, 0x1000, v23
	v_add_u32_e32 v34, 0x1400, v23
	v_add_u32_e32 v35, 0x1800, v23
	v_add_u32_e32 v36, 0x1c00, v23
	v_readlane_b32 s53, v241, 18
	v_readlane_b32 s54, v241, 19
	v_readlane_b32 s55, v241, 20
	v_readlane_b32 s56, v241, 21
	v_readlane_b32 s57, v241, 22
	v_readlane_b32 s58, v241, 23
	v_readlane_b32 s59, v241, 24
	v_readlane_b32 s60, v241, 25
	v_readlane_b32 s61, v241, 26
	v_readlane_b32 s62, v241, 27
	v_readlane_b32 s63, v241, 28
	s_branch .LBB0_574
